# baseline (speedup 1.0000x reference)
.LBB0_2681:
	s_or_b64 exec, exec, s[8:9]
	v_readlane_b32 s8, v255, 13
	v_readlane_b32 s6, v255, 6
	v_readlane_b32 s9, v255, 14
	s_add_i32 s6, s8, s6
	v_readlane_b32 s8, v255, 2
	v_readlane_b32 s7, v255, 17
	s_lshr_b32 s6, s6, 3
	s_mov_b32 s12, s6
	s_sub_i32 s11, s7, s8
	s_waitcnt vmcnt(0)
	v_readfirstlane_b32 s7, v1
	s_mul_i32 s6, s6, s11
	v_readlane_b32 s9, v255, 3
	v_add3_u32 v0, s7, v0, 1
	s_sub_i32 s12, s6, s12
	s_cmp_eq_u32 s7, s12
	s_cbranch_scc0 .Lxb_nf
	s_cmp_eq_u32 s100, 1
	s_cbranch_scc0 .Lxb_nf
	buffer_wbl2 sc1
.Lxb_nf:
	v_cmp_eq_u32_e32 vcc, s6, v0
	s_and_saveexec_b64 s[6:7], vcc
	s_cbranch_execz .LBB0_2684
	s_mov_b64 s[8:9], exec
	v_mbcnt_lo_u32_b32 v0, s8, 0
	v_mbcnt_hi_u32_b32 v0, s9, v0
	v_cmp_eq_u32_e32 vcc, 0, v0
	s_and_b64 s[12:13], exec, vcc
	s_mov_b64 exec, s[12:13]
	s_cbranch_execz .LBB0_2684
	s_bcnt1_i32_b64 s8, s[8:9]
	v_mov_b32_e32 v0, s8
	s_cmp_eq_u32 s100, 1
	s_cbranch_scc0 .Lxb_top
	buffer_wbl2 sc1
	s_waitcnt vmcnt(0)
